# stack ST4: ST2 plus sample_resid_units K-loop issues all operand loads at once (one wait instead of ~20 counted waits)
# baseline (speedup 1.0000x reference)
; template <int K> __device__ __forceinline__ void sample_resid_units(LAS unsigned char* lds, const bf16* Aop, int lda, const bf16* Bt, int ldb, bf16* X, const float* gate, float scale,
;                                                    bf16* XB, float* SSQ, const float* gam, int tid, int vcu, int G) {
;     ...
;     for (int un = vcu; un < 256; un += G) {
;         const int rt = un >> 4, cs = un & 15, pn = cs >> 2, wc = cs & 3; const size_t row0 = (size_t)NPROMPT + 16 * rt;
;         constexpr int kper = K >> 3; const int kbeg = w * kper;
;         f32x4 acc[4];
; #pragma unroll
;         for (int ct = 0; ct < 4; ++ct) acc[ct] = (f32x4){0.f, 0.f, 0.f, 0.f};
;         const bf16* ap = Aop + (row0 + qq) * (size_t)lda + kbeg + 8 * q4;
;         const bf16* bp = Bt + (size_t)(256 * pn + 32 * wc + qq) * ldb + kbeg + 8 * q4;
; #pragma unroll 4
;         for (int k0 = 0; k0 < kper; k0 += 32) {
;             const bf16x8 af = *(const bf16x8*)(ap + k0);
; #pragma unroll
;             for (int ct = 0; ct < 4; ++ct) { const bf16x8 bf = *(const bf16x8*)(bp + (size_t)(128 * (ct >> 1) + 16 * (ct & 1)) * ldb + k0);
;                 acc[ct] = __builtin_amdgcn_mfma_f32_16x16x32_bf16(bf, af, acc[ct], 0, 0, 0); } }
.LBB0_531:
	s_and_b32 s6, s20, -16
	s_ashr_i32 s7, s6, 31
	s_add_u32 s18, s6, 0x8000
	s_addc_u32 s19, s7, 0
	s_lshl_b32 s6, s20, 6
	s_and_b32 s8, s6, 0x300
	s_and_b32 s29, s21, 0x60
	s_or_b32 s6, s29, s8
	v_or_b32_e32 v6, s6, v4
	v_mul_u32_u24_e32 v6, 0xb00, v6
	v_lshlrev_b32_e32 v6, 1, v6
	v_lshl_add_u64 v[72:73], v[10:11], 0, v[6:7]
	v_or_b32_e32 v14, s18, v4
	global_load_dwordx4 v[24:27], v[72:73], off
	v_mad_u64_u32 v[74:75], s[6:7], v14, s23, v[8:9]
	v_add_co_u32_e64 v76, s[6:7], s24, v72
	v_mad_i32_i24 v75, s19, v16, v75
	s_nop 0
	v_addc_co_u32_e64 v77, s[6:7], 0, v73, s[6:7]
	global_load_dwordx4 v[28:31], v[74:75], off
	global_load_dwordx4 v[32:35], v[74:75], off offset:64
	global_load_dwordx4 v[36:39], v[76:77], off
	global_load_dwordx4 v[40:43], v[72:73], off offset:64
	v_add_co_u32_e64 v78, s[6:7], s25, v72
	v_add_u32_e32 v6, s8, v1
	s_nop 0
	v_addc_co_u32_e64 v79, s[6:7], 0, v73, s[6:7]
	v_add_co_u32_e64 v80, s[6:7], s27, v72
	global_load_dwordx4 v[44:47], v[78:79], off
	global_load_dwordx4 v[48:51], v[72:73], off offset:640
	v_addc_co_u32_e64 v81, s[6:7], 0, v73, s[6:7]
	global_load_dwordx4 v[52:55], v[78:79], off offset:64
	global_load_dwordx4 v[56:59], v[80:81], off
	global_load_dwordx4 v[60:63], v[78:79], off offset:640
	v_mov_b32_e32 v15, s19
	global_load_dwordx4 v[64:67], v[76:77], off offset:64
	global_load_dwordx4 v[68:71], v[80:81], off offset:64
	global_load_dwordx4 v[82:85], v[74:75], off offset:128
	global_load_dwordx4 v[86:89], v[72:73], off offset:128
	global_load_dwordx4 v[90:93], v[76:77], off offset:128
	global_load_dwordx4 v[94:97], v[78:79], off offset:128
	global_load_dwordx4 v[98:101], v[80:81], off offset:128
	global_load_dwordx4 v[102:105], v[74:75], off offset:192
	global_load_dwordx4 v[106:109], v[72:73], off offset:192
	global_load_dwordx4 v[110:113], v[76:77], off offset:192
	global_load_dwordx4 v[114:117], v[78:79], off offset:192
	global_load_dwordx4 v[118:121], v[80:81], off offset:192
	global_load_dwordx4 v[122:125], v[74:75], off offset:256
	global_load_dwordx4 v[126:129], v[72:73], off offset:256
	global_load_dwordx4 v[130:133], v[76:77], off offset:256
	global_load_dwordx4 v[134:137], v[78:79], off offset:256
	global_load_dwordx4 v[138:141], v[80:81], off offset:256
	global_load_dwordx4 v[142:145], v[74:75], off offset:320
	global_load_dwordx4 v[146:149], v[72:73], off offset:320
	global_load_dwordx4 v[150:153], v[76:77], off offset:320
	global_load_dwordx4 v[154:157], v[78:79], off offset:320
	global_load_dwordx4 v[158:161], v[80:81], off offset:320
	global_load_dwordx4 v[162:165], v[74:75], off offset:384
	global_load_dwordx4 v[166:169], v[72:73], off offset:384
	global_load_dwordx4 v[170:173], v[76:77], off offset:384
	global_load_dwordx4 v[174:177], v[78:79], off offset:384
	global_load_dwordx4 v[178:181], v[80:81], off offset:384
	global_load_dwordx4 v[182:185], v[74:75], off offset:448
	global_load_dwordx4 v[186:189], v[72:73], off offset:448
	global_load_dwordx4 v[190:193], v[76:77], off offset:448
	global_load_dwordx4 v[194:197], v[78:79], off offset:448
	global_load_dwordx4 v[198:201], v[80:81], off offset:448
	global_load_dwordx4 v[202:205], v[74:75], off offset:512
	global_load_dwordx4 v[206:209], v[72:73], off offset:512
	global_load_dwordx4 v[210:213], v[76:77], off offset:512
	global_load_dwordx4 v[214:217], v[78:79], off offset:512
	global_load_dwordx4 v[218:221], v[80:81], off offset:512
	global_load_dwordx4 v[222:225], v[74:75], off offset:576
	global_load_dwordx4 v[226:229], v[72:73], off offset:576
	global_load_dwordx4 v[230:233], v[76:77], off offset:576
	global_load_dwordx4 v[234:237], v[78:79], off offset:576
	global_load_dwordx4 v[238:241], v[80:81], off offset:576
	global_load_dwordx4 v[242:245], v[74:75], off offset:640
	global_load_dwordx4 v[246:249], v[76:77], off offset:640
	global_load_dwordx4 v[250:253], v[80:81], off offset:640
	s_barrier
; __device__ __forceinline__ unsigned pk2(float lo, float hi) { unsigned r; asm("v_cvt_pk_bf16_f32 %0, %1, %2" : "=v"(r) : "v"(lo), "v"(hi)); return r; }
; template <int K> __device__ __forceinline__ void sample_resid_units(LAS unsigned char* lds, const bf16* Aop, int lda, const bf16* Bt, int ldb, bf16* X, const float* gate, float scale,
;                                                    bf16* XB, float* SSQ, const float* gam, int tid, int vcu, int G) {
;     ...
;         for (int k0 = 0; k0 < kper; k0 += 32) {
;             const bf16x8 af = *(const bf16x8*)(ap + k0);
; #pragma unroll
;             for (int ct = 0; ct < 4; ++ct) { const bf16x8 bf = *(const bf16x8*)(bp + (size_t)(128 * (ct >> 1) + 16 * (ct & 1)) * ldb + k0);
;                 acc[ct] = __builtin_amdgcn_mfma_f32_16x16x32_bf16(bf, af, acc[ct], 0, 0, 0); } }
;         __syncthreads();
; #pragma unroll
;         for (int ct = 0; ct < 4; ++ct)
; #pragma unroll
;             for (int i = 0; i < 4; ++i) P[((w * 4 + ct) * 4 + i) * 64 + lane] = acc[ct][i];
;         __syncthreads();
;         const int r = tid & 15, ct = tid >> 7, np = (tid >> 4) & 7, i0 = 2 * (np & 1), ln = r + 16 * (np >> 1);
;         float s0 = 0.f, s1 = 0.f;
; #pragma unroll
;         for (int ww = 0; ww < 8; ++ww) { s0 += P[((ww * 4 + ct) * 4 + i0) * 64 + ln]; s1 += P[((ww * 4 + ct) * 4 + i0 + 1) * 64 + ln]; }
;         const size_t row = row0 + r; const int sq = 16 + (int)((row - NPROMPT) >> 3);
;         const int col = 256 * pn + 128 * (ct >> 1) + 32 * wc + 16 * (ct & 1) + 2 * np;
;         const unsigned xw = *(const unsigned*)(X + row * DM + col);
;         const float g0 = gate[(size_t)sq * NMOD + col], g1 = gate[(size_t)sq * NMOD + col + 1];
;         const float x0 = bflo(xw) + scale * g0 * s0, x1 = bfhi(xw) + scale * g1 * s1;
;         *(unsigned*)(X + row * DM + col) = pk2(x0, x1);
;         const float m0 = gam[(size_t)sq * DM + col], m1 = gam[(size_t)sq * DM + col + 1];
;         *(unsigned*)(XB + row * DM + col) = pk2(x0 * m0, x1 * m1);
;         float ss = x0 * x0 + x1 * x1;
;         ss += __shfl_xor(ss, 16); ss += __shfl_xor(ss, 32);
;         if (lane < 16) R[r * 8 + w] = ss;
	s_waitcnt vmcnt(0)
	v_mfma_f32_16x16x32_bf16 v[24:27], v[24:27], v[28:31], 0
	v_mfma_f32_16x16x32_bf16 v[36:39], v[36:39], v[28:31], 0
	v_mfma_f32_16x16x32_bf16 v[44:47], v[44:47], v[28:31], 0
	v_mfma_f32_16x16x32_bf16 v[56:59], v[56:59], v[28:31], 0
	v_mfma_f32_16x16x32_bf16 v[24:27], v[40:43], v[32:35], v[24:27]
	v_mfma_f32_16x16x32_bf16 v[36:39], v[64:67], v[32:35], v[36:39]
	v_mfma_f32_16x16x32_bf16 v[44:47], v[52:55], v[32:35], v[44:47]
	v_mfma_f32_16x16x32_bf16 v[56:59], v[68:71], v[32:35], v[56:59]
	v_mfma_f32_16x16x32_bf16 v[24:27], v[86:89], v[82:85], v[24:27]
	v_mfma_f32_16x16x32_bf16 v[36:39], v[90:93], v[82:85], v[36:39]
	v_mfma_f32_16x16x32_bf16 v[44:47], v[94:97], v[82:85], v[44:47]
	v_mfma_f32_16x16x32_bf16 v[56:59], v[98:101], v[82:85], v[56:59]
	v_mfma_f32_16x16x32_bf16 v[24:27], v[106:109], v[102:105], v[24:27]
	v_mfma_f32_16x16x32_bf16 v[36:39], v[110:113], v[102:105], v[36:39]
	v_mfma_f32_16x16x32_bf16 v[44:47], v[114:117], v[102:105], v[44:47]
	v_mfma_f32_16x16x32_bf16 v[56:59], v[118:121], v[102:105], v[56:59]
	v_mfma_f32_16x16x32_bf16 v[24:27], v[126:129], v[122:125], v[24:27]
	v_mfma_f32_16x16x32_bf16 v[36:39], v[130:133], v[122:125], v[36:39]
	v_mfma_f32_16x16x32_bf16 v[44:47], v[134:137], v[122:125], v[44:47]
	v_mfma_f32_16x16x32_bf16 v[56:59], v[138:141], v[122:125], v[56:59]
	v_mfma_f32_16x16x32_bf16 v[24:27], v[146:149], v[142:145], v[24:27]
	v_mfma_f32_16x16x32_bf16 v[36:39], v[150:153], v[142:145], v[36:39]
	v_mfma_f32_16x16x32_bf16 v[44:47], v[154:157], v[142:145], v[44:47]
	v_mfma_f32_16x16x32_bf16 v[56:59], v[158:161], v[142:145], v[56:59]
	v_mfma_f32_16x16x32_bf16 v[24:27], v[166:169], v[162:165], v[24:27]
	v_mfma_f32_16x16x32_bf16 v[36:39], v[170:173], v[162:165], v[36:39]
	v_mfma_f32_16x16x32_bf16 v[44:47], v[174:177], v[162:165], v[44:47]
	v_mfma_f32_16x16x32_bf16 v[56:59], v[178:181], v[162:165], v[56:59]
	v_mfma_f32_16x16x32_bf16 v[24:27], v[186:189], v[182:185], v[24:27]
	v_mfma_f32_16x16x32_bf16 v[36:39], v[190:193], v[182:185], v[36:39]
	v_mfma_f32_16x16x32_bf16 v[44:47], v[194:197], v[182:185], v[44:47]
	v_mfma_f32_16x16x32_bf16 v[56:59], v[198:201], v[182:185], v[56:59]
	v_mfma_f32_16x16x32_bf16 v[24:27], v[206:209], v[202:205], v[24:27]
	v_mfma_f32_16x16x32_bf16 v[36:39], v[210:213], v[202:205], v[36:39]
	v_mfma_f32_16x16x32_bf16 v[44:47], v[214:217], v[202:205], v[44:47]
	v_mfma_f32_16x16x32_bf16 v[56:59], v[218:221], v[202:205], v[56:59]
	v_mfma_f32_16x16x32_bf16 v[24:27], v[226:229], v[222:225], v[24:27]
	v_mfma_f32_16x16x32_bf16 v[36:39], v[230:233], v[222:225], v[36:39]
	v_mfma_f32_16x16x32_bf16 v[44:47], v[234:237], v[222:225], v[44:47]
	v_mfma_f32_16x16x32_bf16 v[56:59], v[238:241], v[222:225], v[56:59]
	v_mfma_f32_16x16x32_bf16 v[24:27], v[48:51], v[242:245], v[24:27]
	v_mfma_f32_16x16x32_bf16 v[36:39], v[246:249], v[242:245], v[36:39]
	v_mfma_f32_16x16x32_bf16 v[44:47], v[60:63], v[242:245], v[44:47]
	v_mfma_f32_16x16x32_bf16 v[56:59], v[250:253], v[242:245], v[56:59]
	s_nop 7
	s_nop 3
	ds_write2st64_b32 v17, v24, v25 offset1:1
	ds_write2st64_b32 v17, v26, v27 offset0:2 offset1:3
	ds_write2st64_b32 v17, v36, v37 offset0:4 offset1:5
	ds_write2st64_b32 v17, v38, v39 offset0:6 offset1:7
	ds_write2st64_b32 v17, v44, v45 offset0:8 offset1:9
	ds_write2st64_b32 v17, v46, v47 offset0:10 offset1:11
	ds_write2st64_b32 v17, v56, v57 offset0:12 offset1:13
	ds_write2st64_b32 v17, v58, v59 offset0:14 offset1:15
	v_or_b32_e32 v24, s29, v6
	v_lshlrev_b64 v[26:27], 11, v[14:15]
	v_ashrrev_i32_e32 v25, 31, v24
	v_lshlrev_b64 v[14:15], 29, v[14:15]
	v_lshl_add_u64 v[28:29], s[0:1], 0, v[26:27]
	v_lshlrev_b64 v[30:31], 1, v[24:25]
	v_add_u32_e32 v14, 0xfffff010, v15
	v_lshl_add_u64 v[28:29], v[28:29], 0, v[30:31]
	v_mad_i64_i32 v[32:33], s[6:7], v14, s28, v[12:13]
	v_lshlrev_b64 v[24:25], 2, v[24:25]
	s_waitcnt lgkmcnt(0)
	s_barrier
	v_lshl_add_u64 v[32:33], v[32:33], 0, v[24:25]
	global_load_dword v6, v[28:29], off
	global_load_dwordx2 v[34:35], v[32:33], off
	v_ashrrev_i32_e32 v15, 31, v14
	v_lshlrev_b64 v[14:15], 12, v[14:15]
	v_lshl_add_u64 v[14:15], s[16:17], 0, v[14:15]
	v_lshl_add_u64 v[14:15], v[14:15], 0, v[24:25]
	global_load_dwordx2 v[14:15], v[14:15], off
	v_cmp_lt_i32_e64 s[6:7], v20, v21
	s_nop 1
	v_cndmask_b32_e64 v24, v19, v20, s[6:7]
	v_lshlrev_b32_e32 v49, 2, v24
	ds_read2st64_b32 v[24:25], v18 offset1:1
	ds_read2st64_b32 v[32:33], v18 offset0:16 offset1:17
	ds_read2st64_b32 v[36:37], v18 offset0:32 offset1:33
	ds_read2st64_b32 v[38:39], v18 offset0:48 offset1:49
	ds_read2st64_b32 v[40:41], v18 offset0:64 offset1:65
	ds_read2st64_b32 v[42:43], v18 offset0:80 offset1:81
	ds_read2st64_b32 v[44:45], v18 offset0:96 offset1:97
	ds_read2st64_b32 v[46:47], v18 offset0:112 offset1:113
	s_waitcnt lgkmcnt(7)
	v_add_f32_e32 v25, 0, v25
	v_add_f32_e32 v24, 0, v24
	s_waitcnt lgkmcnt(6)
	v_add_f32_e32 v25, v25, v33
	v_add_f32_e32 v24, v24, v32
	s_waitcnt lgkmcnt(5)
	v_add_f32_e32 v25, v25, v37
	v_add_f32_e32 v24, v24, v36
	s_waitcnt lgkmcnt(4)
	v_add_f32_e32 v25, v25, v39
	v_add_f32_e32 v24, v24, v38
	s_waitcnt lgkmcnt(3)
	v_add_f32_e32 v25, v25, v41
	v_add_f32_e32 v24, v24, v40
	s_waitcnt lgkmcnt(2)
	v_add_f32_e32 v25, v25, v43
	v_add_f32_e32 v24, v24, v42
	s_waitcnt lgkmcnt(1)
	v_add_f32_e32 v25, v25, v45
	v_add_f32_e32 v24, v24, v44
	s_waitcnt lgkmcnt(0)
	v_add_f32_e32 v25, v25, v47
	v_add_f32_e32 v24, v24, v46
	v_cmp_lt_i32_e64 s[6:7], v22, v21
	s_waitcnt vmcnt(2)
	v_lshlrev_b32_e32 v32, 16, v6
	s_waitcnt vmcnt(1)
	v_mul_f32_e32 v33, 0.5, v34
	v_and_b32_e32 v6, 0xffff0000, v6
	v_mul_f32_e32 v34, 0.5, v35
	v_fmac_f32_e32 v6, v25, v34
	v_fmac_f32_e32 v32, v24, v33
	v_mul_f32_e32 v24, v6, v6
	v_fmac_f32_e32 v24, v32, v32
	ds_bpermute_b32 v25, v49, v24
	v_cndmask_b32_e64 v48, v19, v22, s[6:7]
	v_cvt_pk_bf16_f32 v33, v32, v6
	s_waitcnt vmcnt(0)
	v_mul_f32_e32 v32, v32, v14
	v_mul_f32_e32 v15, v6, v15
	s_waitcnt lgkmcnt(0)
	v_add_f32_e32 v6, v24, v25
	v_lshlrev_b32_e32 v14, 2, v48
	ds_bpermute_b32 v14, v14, v6
	v_lshl_add_u64 v[24:25], s[10:11], 0, v[26:27]
	v_lshl_add_u64 v[24:25], v[24:25], 0, v[30:31]
	global_store_dword v[28:29], v33, off
	v_cvt_pk_bf16_f32 v15, v32, v15
	global_store_dword v[24:25], v15, off
	s_and_saveexec_b64 s[6:7], vcc
	s_cbranch_execz .LBB0_533
	s_waitcnt lgkmcnt(0)
	v_add_f32_e32 v6, v6, v14
	ds_write_b32 v23, v6 offset:32768
